# v6 + EpiResid epilogues of the three 256x256 residual GEMMs: 14-deep window of outstanding src loads with counted vmcnt, stores deferred to the tile end (was: one load pair + vmcnt(0) per 16x16 block)
# baseline (speedup 1.0000x reference)
.LBB0_799:
	v_add_u32_e32 v151, s27, v133
	v_add_u32_e32 v140, s26, v149
	s_mov_b32 s26, 0x8000
	v_add_u32_e32 v142, 0xffff8000, v151
	v_ashrrev_i32_e32 v143, 31, v151
	v_cmp_gt_i32_e32 vcc, s26, v151
	v_readlane_b32 s64, v254, 27
	v_ashrrev_i32_e32 v141, 31, v140
	v_cndmask_b32_e32 v143, 0, v143, vcc
	v_cndmask_b32_e32 v142, v142, v151, vcc
	v_lshlrev_b64 v[144:145], 12, v[142:143]
	v_min_i32_e32 v142, 0x8000, v151
	v_ashrrev_i32_e32 v142, 12, v142
	v_mul_i32_i24_e32 v142, 0x2400, v142
	v_ashrrev_i32_e32 v143, 31, v142
	v_readlane_b32 s65, v254, 28
	v_lshlrev_b64 v[140:141], 2, v[140:141]
	v_mov_b32_e32 v152, s9
	v_lshl_add_u64 v[142:143], v[142:143], 2, s[64:65]
	v_mov_b32_e32 v153, s11
	v_mov_b32_e32 v154, s8
	v_mov_b32_e32 v155, s10
	v_lshl_add_u64 v[168:169], v[142:143], 0, v[140:141]
	s_movk_i32 s27, 0x2000
	v_cndmask_b32_e32 v147, v152, v153, vcc
	v_cndmask_b32_e32 v146, v154, v155, vcc
	v_add_co_u32_e64 v142, s[6:7], s27, v168
	v_lshl_add_u64 v[146:147], v[146:147], 0, v[144:145]
	s_nop 0
	v_addc_co_u32_e64 v143, s[6:7], 0, v169, s[6:7]
	v_lshl_add_u64 v[142:143], v[146:147], 0, v[140:141]
	v_readlane_b32 s48, v251, 19
	v_readlane_b32 s52, v251, 23
	v_readlane_b32 s53, v251, 24
	v_readlane_b32 s54, v251, 25
	v_readlane_b32 s55, v251, 26
	v_readlane_b32 s56, v251, 27
	v_readlane_b32 s57, v251, 28
	v_readlane_b32 s58, v251, 29
	v_readlane_b32 s59, v251, 30
	v_readlane_b32 s60, v251, 31
	v_readlane_b32 s61, v251, 32
	v_readlane_b32 s62, v251, 33
	v_readlane_b32 s63, v251, 34
	s_mov_b64 s[52:53], s[56:57]
	s_mov_b64 s[54:55], s[58:59]
	v_mov_b32_e32 v156, s55
	v_mov_b32_e32 v157, s53
	v_mov_b32_e32 v158, s54
	v_mov_b32_e32 v159, s52
	v_cndmask_b32_e32 v147, v156, v157, vcc
	v_cndmask_b32_e32 v146, v158, v159, vcc
	v_lshl_add_u64 v[144:145], v[146:147], 0, v[144:145]
	v_lshl_add_u64 v[144:145], v[144:145], 0, v[140:141]
	s_mov_b64 s[38:39], 0x2000
	v_lshl_add_u64 v[146:147], v[168:169], 0, s[38:39]
	s_movk_i32 s30, 0x7ff0
	v_cmp_gt_i32_e32 vcc, s30, v151
	s_movk_i32 s31, 0x7fe0
	s_movk_i32 s34, 0x7fd0
	v_readlane_b32 s49, v251, 20
	v_readlane_b32 s50, v251, 21
	v_readlane_b32 s51, v251, 22
	s_mov_b64 s[56:57], s[60:61]
	s_mov_b64 s[58:59], s[62:63]
	v_readlane_b32 s48, v251, 3
	v_readlane_b32 s49, v251, 4
	v_readlane_b32 s50, v251, 5
	v_readlane_b32 s51, v251, 6
	v_readlane_b32 s52, v251, 7
	v_readlane_b32 s53, v251, 8
	v_readlane_b32 s54, v251, 9
	v_readlane_b32 s55, v251, 10
	v_readlane_b32 s56, v251, 11
	v_readlane_b32 s57, v251, 12
	v_readlane_b32 s58, v251, 13
	v_readlane_b32 s59, v251, 14
	v_readlane_b32 s60, v251, 15
	v_readlane_b32 s61, v251, 16
	v_readlane_b32 s62, v251, 17
	v_readlane_b32 s63, v251, 18
	v_readlane_b32 s48, v252, 4
	v_readlane_b32 s49, v252, 5
	v_readlane_b32 s50, v252, 6
	v_readlane_b32 s51, v252, 7
	v_readlane_b32 s52, v252, 8
	v_readlane_b32 s53, v252, 9
	v_readlane_b32 s54, v252, 10
	v_readlane_b32 s55, v252, 11
	v_readlane_b32 s56, v252, 12
	v_readlane_b32 s57, v252, 13
	v_readlane_b32 s58, v252, 14
	v_readlane_b32 s59, v252, 15
	v_readlane_b32 s60, v252, 16
	v_readlane_b32 s61, v252, 17
	v_readlane_b32 s62, v252, 18
	v_readlane_b32 s63, v252, 19
	s_mov_b64 s[94:95], 0x10000
	s_mov_b64 s[96:97], 0x50000
	global_load_dwordx4 v[152:155], v[146:147], off
	global_load_dwordx4 v[156:159], v[146:147], off offset:64
	global_load_dwordx4 v[160:163], v[146:147], off offset:512
	global_load_dwordx4 v[164:167], v[146:147], off offset:576
	v_mov_b64_e32 v[248:249], v[142:143]
	v_mov_b64_e32 v[140:141], v[144:145]
	global_load_dwordx4 v[168:171], v[248:249], off
	global_load_dwordx4 v[172:175], v[248:249], off offset:64
	global_load_dwordx4 v[176:179], v[248:249], off offset:512
	global_load_dwordx4 v[204:207], v[248:249], off offset:576
	v_lshl_add_u64 v[248:249], v[248:249], 0, s[94:95]
	global_load_dwordx4 v[208:211], v[248:249], off
	global_load_dwordx4 v[212:215], v[248:249], off offset:64
	global_load_dwordx4 v[216:219], v[248:249], off offset:512
	global_load_dwordx4 v[220:223], v[248:249], off offset:576
	v_lshl_add_u64 v[248:249], v[248:249], 0, s[94:95]
	global_load_dwordx4 v[224:227], v[248:249], off
	global_load_dwordx4 v[228:231], v[248:249], off offset:64
	global_load_dwordx4 v[232:235], v[248:249], off offset:512
	global_load_dwordx4 v[236:239], v[248:249], off offset:576
	v_lshl_add_u64 v[248:249], v[248:249], 0, s[94:95]
	global_load_dwordx4 v[240:243], v[248:249], off
	global_load_dwordx4 v[244:247], v[248:249], off offset:64
	s_waitcnt vmcnt(13)
	v_pk_mul_f32 v[154:155], v[154:155], 0.5 op_sel_hi:[1,0]
	v_pk_mul_f32 v[152:153], v[152:153], 0.5 op_sel_hi:[1,0]
	v_pk_mul_f32 v[158:159], v[158:159], 0.5 op_sel_hi:[1,0]
	v_pk_mul_f32 v[156:157], v[156:157], 0.5 op_sel_hi:[1,0]
	v_pk_mul_f32 v[162:163], v[162:163], 0.5 op_sel_hi:[1,0]
	v_pk_mul_f32 v[160:161], v[160:161], 0.5 op_sel_hi:[1,0]
	v_pk_mul_f32 v[166:167], v[166:167], 0.5 op_sel_hi:[1,0]
	v_pk_mul_f32 v[164:165], v[164:165], 0.5 op_sel_hi:[1,0]
	v_pk_fma_f32 v[126:127], v[126:127], v[154:155], v[170:171]
	v_pk_fma_f32 v[124:125], v[124:125], v[152:153], v[168:169]
	global_load_dwordx4 v[168:171], v[248:249], off offset:512
	s_waitcnt vmcnt(13)
	v_pk_fma_f32 v[122:123], v[122:123], v[158:159], v[174:175]
	v_pk_fma_f32 v[120:121], v[120:121], v[156:157], v[172:173]
	global_load_dwordx4 v[172:175], v[248:249], off offset:576
	s_waitcnt vmcnt(13)
	v_pk_fma_f32 v[94:95], v[94:95], v[162:163], v[178:179]
	v_pk_fma_f32 v[92:93], v[92:93], v[160:161], v[176:177]
	v_lshl_add_u64 v[248:249], v[248:249], 0, s[96:97]
	global_load_dwordx4 v[176:179], v[248:249], off
	s_waitcnt vmcnt(13)
	v_pk_fma_f32 v[90:91], v[90:91], v[166:167], v[206:207]
	v_pk_fma_f32 v[88:89], v[88:89], v[164:165], v[204:205]
	global_load_dwordx4 v[204:207], v[248:249], off offset:64
	s_waitcnt vmcnt(13)
	v_pk_fma_f32 v[118:119], v[118:119], v[154:155], v[210:211]
	v_pk_fma_f32 v[116:117], v[116:117], v[152:153], v[208:209]
	global_load_dwordx4 v[208:211], v[248:249], off offset:512
	s_waitcnt vmcnt(13)
	v_pk_fma_f32 v[114:115], v[114:115], v[158:159], v[214:215]
	v_pk_fma_f32 v[112:113], v[112:113], v[156:157], v[212:213]
	global_load_dwordx4 v[212:215], v[248:249], off offset:576
	s_waitcnt vmcnt(13)
	v_pk_fma_f32 v[86:87], v[86:87], v[162:163], v[218:219]
	v_pk_fma_f32 v[84:85], v[84:85], v[160:161], v[216:217]
	v_lshl_add_u64 v[248:249], v[248:249], 0, s[94:95]
	global_load_dwordx4 v[216:219], v[248:249], off
	s_waitcnt vmcnt(13)
	v_pk_fma_f32 v[82:83], v[82:83], v[166:167], v[222:223]
	v_pk_fma_f32 v[80:81], v[80:81], v[164:165], v[220:221]
	global_load_dwordx4 v[220:223], v[248:249], off offset:64
	s_waitcnt vmcnt(13)
	v_pk_fma_f32 v[110:111], v[110:111], v[154:155], v[226:227]
	v_pk_fma_f32 v[108:109], v[108:109], v[152:153], v[224:225]
	global_load_dwordx4 v[224:227], v[248:249], off offset:512
	s_waitcnt vmcnt(13)
	v_pk_fma_f32 v[106:107], v[106:107], v[158:159], v[230:231]
	v_pk_fma_f32 v[104:105], v[104:105], v[156:157], v[228:229]
	global_load_dwordx4 v[228:231], v[248:249], off offset:576
	s_waitcnt vmcnt(13)
	v_pk_fma_f32 v[78:79], v[78:79], v[162:163], v[234:235]
	v_pk_fma_f32 v[76:77], v[76:77], v[160:161], v[232:233]
	v_lshl_add_u64 v[248:249], v[248:249], 0, s[94:95]
	global_load_dwordx4 v[232:235], v[248:249], off
	s_waitcnt vmcnt(13)
	v_pk_fma_f32 v[74:75], v[74:75], v[166:167], v[238:239]
	v_pk_fma_f32 v[72:73], v[72:73], v[164:165], v[236:237]
	global_load_dwordx4 v[236:239], v[248:249], off offset:64
	s_waitcnt vmcnt(13)
	v_pk_fma_f32 v[102:103], v[102:103], v[154:155], v[242:243]
	v_pk_fma_f32 v[100:101], v[100:101], v[152:153], v[240:241]
	global_load_dwordx4 v[240:243], v[248:249], off offset:512
	s_waitcnt vmcnt(13)
	v_pk_fma_f32 v[98:99], v[98:99], v[158:159], v[246:247]
	v_pk_fma_f32 v[96:97], v[96:97], v[156:157], v[244:245]
	global_load_dwordx4 v[244:247], v[248:249], off offset:576
	s_waitcnt vmcnt(13)
	v_pk_fma_f32 v[70:71], v[70:71], v[162:163], v[170:171]
	v_pk_fma_f32 v[68:69], v[68:69], v[160:161], v[168:169]
	v_lshl_add_u64 v[248:249], v[248:249], 0, s[94:95]
	global_load_dwordx4 v[168:171], v[248:249], off
	s_waitcnt vmcnt(13)
	v_pk_fma_f32 v[66:67], v[66:67], v[166:167], v[174:175]
	v_pk_fma_f32 v[64:65], v[64:65], v[164:165], v[172:173]
	global_load_dwordx4 v[172:175], v[248:249], off offset:64
	s_waitcnt vmcnt(13)
	v_pk_fma_f32 v[62:63], v[62:63], v[154:155], v[178:179]
	v_pk_fma_f32 v[60:61], v[60:61], v[152:153], v[176:177]
	global_load_dwordx4 v[176:179], v[248:249], off offset:512
	s_waitcnt vmcnt(13)
	v_pk_fma_f32 v[58:59], v[58:59], v[158:159], v[206:207]
	v_pk_fma_f32 v[56:57], v[56:57], v[156:157], v[204:205]
	global_load_dwordx4 v[204:207], v[248:249], off offset:576
	s_waitcnt vmcnt(13)
	v_pk_fma_f32 v[30:31], v[30:31], v[162:163], v[210:211]
	v_pk_fma_f32 v[28:29], v[28:29], v[160:161], v[208:209]
	s_waitcnt vmcnt(12)
	v_pk_fma_f32 v[26:27], v[26:27], v[166:167], v[214:215]
	v_pk_fma_f32 v[24:25], v[24:25], v[164:165], v[212:213]
	s_waitcnt vmcnt(11)
	v_pk_fma_f32 v[54:55], v[54:55], v[154:155], v[218:219]
	v_pk_fma_f32 v[52:53], v[52:53], v[152:153], v[216:217]
	s_waitcnt vmcnt(10)
	v_pk_fma_f32 v[50:51], v[50:51], v[158:159], v[222:223]
	v_pk_fma_f32 v[48:49], v[48:49], v[156:157], v[220:221]
	s_waitcnt vmcnt(9)
	v_pk_fma_f32 v[22:23], v[22:23], v[162:163], v[226:227]
	v_pk_fma_f32 v[20:21], v[20:21], v[160:161], v[224:225]
	s_waitcnt vmcnt(8)
	v_pk_fma_f32 v[18:19], v[18:19], v[166:167], v[230:231]
	v_pk_fma_f32 v[16:17], v[16:17], v[164:165], v[228:229]
	s_waitcnt vmcnt(7)
	v_pk_fma_f32 v[46:47], v[46:47], v[154:155], v[234:235]
	v_pk_fma_f32 v[44:45], v[44:45], v[152:153], v[232:233]
	s_waitcnt vmcnt(6)
	v_pk_fma_f32 v[42:43], v[42:43], v[158:159], v[238:239]
	v_pk_fma_f32 v[40:41], v[40:41], v[156:157], v[236:237]
	s_waitcnt vmcnt(5)
	v_pk_fma_f32 v[14:15], v[14:15], v[162:163], v[242:243]
	v_pk_fma_f32 v[12:13], v[12:13], v[160:161], v[240:241]
	s_waitcnt vmcnt(4)
	v_pk_fma_f32 v[10:11], v[10:11], v[166:167], v[246:247]
	v_pk_fma_f32 v[8:9], v[8:9], v[164:165], v[244:245]
	s_waitcnt vmcnt(3)
	v_pk_fma_f32 v[38:39], v[38:39], v[154:155], v[170:171]
	v_pk_fma_f32 v[36:37], v[36:37], v[152:153], v[168:169]
	s_waitcnt vmcnt(2)
	v_pk_fma_f32 v[34:35], v[34:35], v[158:159], v[174:175]
	v_pk_fma_f32 v[32:33], v[32:33], v[156:157], v[172:173]
	s_waitcnt vmcnt(1)
	v_pk_fma_f32 v[6:7], v[6:7], v[162:163], v[178:179]
	v_pk_fma_f32 v[4:5], v[4:5], v[160:161], v[176:177]
	s_waitcnt vmcnt(0)
	v_pk_fma_f32 v[2:3], v[2:3], v[166:167], v[206:207]
	v_pk_fma_f32 v[0:1], v[0:1], v[164:165], v[204:205]
	global_store_dwordx4 v[140:141], v[124:127], off
	global_store_dwordx4 v[140:141], v[120:123], off offset:64
	global_store_dwordx4 v[140:141], v[92:95], off offset:512
	global_store_dwordx4 v[140:141], v[88:91], off offset:576
	v_lshl_add_u64 v[140:141], v[140:141], 0, s[94:95]
	global_store_dwordx4 v[140:141], v[116:119], off
	global_store_dwordx4 v[140:141], v[112:115], off offset:64
	global_store_dwordx4 v[140:141], v[84:87], off offset:512
	global_store_dwordx4 v[140:141], v[80:83], off offset:576
	v_lshl_add_u64 v[140:141], v[140:141], 0, s[94:95]
	global_store_dwordx4 v[140:141], v[108:111], off
	global_store_dwordx4 v[140:141], v[104:107], off offset:64
	global_store_dwordx4 v[140:141], v[76:79], off offset:512
	global_store_dwordx4 v[140:141], v[72:75], off offset:576
	v_lshl_add_u64 v[140:141], v[140:141], 0, s[94:95]
	global_store_dwordx4 v[140:141], v[100:103], off
	global_store_dwordx4 v[140:141], v[96:99], off offset:64
	global_store_dwordx4 v[140:141], v[68:71], off offset:512
	global_store_dwordx4 v[140:141], v[64:67], off offset:576
	v_lshl_add_u64 v[140:141], v[140:141], 0, s[96:97]
	global_store_dwordx4 v[140:141], v[60:63], off
	global_store_dwordx4 v[140:141], v[56:59], off offset:64
	global_store_dwordx4 v[140:141], v[28:31], off offset:512
	global_store_dwordx4 v[140:141], v[24:27], off offset:576
	v_lshl_add_u64 v[140:141], v[140:141], 0, s[94:95]
	global_store_dwordx4 v[140:141], v[52:55], off
	global_store_dwordx4 v[140:141], v[48:51], off offset:64
	global_store_dwordx4 v[140:141], v[20:23], off offset:512
	global_store_dwordx4 v[140:141], v[16:19], off offset:576
	v_lshl_add_u64 v[140:141], v[140:141], 0, s[94:95]
	global_store_dwordx4 v[140:141], v[44:47], off
	global_store_dwordx4 v[140:141], v[40:43], off offset:64
	global_store_dwordx4 v[140:141], v[12:15], off offset:512
	global_store_dwordx4 v[140:141], v[8:11], off offset:576
	v_lshl_add_u64 v[140:141], v[140:141], 0, s[94:95]
	global_store_dwordx4 v[140:141], v[36:39], off
	global_store_dwordx4 v[140:141], v[32:35], off offset:64
	global_store_dwordx4 v[140:141], v[4:7], off offset:512
	global_store_dwordx4 v[140:141], v[0:3], off offset:576
	s_mov_b32 s26, s28
	s_mov_b32 s27, s29
	s_andn2_b64 vcc, exec, s[14:15]
	s_cbranch_vccz .LBB0_811

.LBB0_1831:
	v_add_u32_e32 v146, s26, v133
	v_min_i32_e32 v144, 0x8000, v146
	v_readlane_b32 s48, v251, 19
	v_ashrrev_i32_e32 v144, 12, v144
	v_readlane_b32 s52, v251, 23
	v_readlane_b32 s53, v251, 24
	v_readlane_b32 s54, v251, 25
	v_readlane_b32 s55, v251, 26
	v_readlane_b32 s56, v251, 27
	v_readlane_b32 s57, v251, 28
	v_readlane_b32 s58, v251, 29
	v_readlane_b32 s59, v251, 30
	v_add_u32_e32 v140, s25, v149
	s_mov_b32 s11, 0x8000
	v_mul_i32_i24_e32 v144, 0x2400, v144
	v_readlane_b32 s60, v251, 31
	v_readlane_b32 s61, v251, 32
	v_readlane_b32 s62, v251, 33
	v_readlane_b32 s63, v251, 34
	s_mov_b64 s[52:53], s[56:57]
	v_readlane_b32 s30, v254, 27
	v_ashrrev_i32_e32 v141, 31, v140
	v_add_u32_e32 v142, 0xffff8000, v146
	v_ashrrev_i32_e32 v143, 31, v146
	v_cmp_gt_i32_e32 vcc, s11, v146
	v_ashrrev_i32_e32 v145, 31, v144
	s_mov_b64 s[54:55], s[58:59]
	v_readlane_b32 s31, v254, 28
	v_cndmask_b32_e32 v143, 0, v143, vcc
	v_cndmask_b32_e32 v142, v142, v146, vcc
	v_mov_b32_e32 v147, s55
	v_mov_b32_e32 v151, s53
	v_mov_b32_e32 v152, s54
	v_mov_b32_e32 v153, s52
	v_lshl_add_u64 v[144:145], v[144:145], 2, s[30:31]
	v_lshlrev_b64 v[140:141], 2, v[140:141]
	v_lshlrev_b64 v[142:143], 12, v[142:143]
	v_cndmask_b32_e32 v155, v147, v151, vcc
	v_cndmask_b32_e32 v154, v152, v153, vcc
	v_lshl_add_u64 v[144:145], v[144:145], 0, v[140:141]
	s_movk_i32 s27, 0x5000
	v_lshl_add_u64 v[142:143], v[154:155], 0, v[142:143]
	v_add_co_u32_e32 v154, vcc, s27, v144
	v_lshl_add_u64 v[142:143], v[142:143], 0, v[140:141]
	s_nop 0
	v_addc_co_u32_e32 v155, vcc, 0, v145, vcc
	s_nop 0
	s_mov_b64 s[28:29], 0x5000
	v_lshl_add_u64 v[144:145], v[144:145], 0, s[28:29]
	s_movk_i32 s13, 0x7ff0
	v_cmp_gt_i32_e32 vcc, s13, v146
	s_movk_i32 s25, 0x7fe0
	s_movk_i32 s26, 0x7fd0
	v_readlane_b32 s49, v251, 20
	v_readlane_b32 s50, v251, 21
	v_readlane_b32 s51, v251, 22
	s_mov_b64 s[56:57], s[60:61]
	s_mov_b64 s[58:59], s[62:63]
	s_mov_b64 s[94:95], 0x10000
	s_mov_b64 s[96:97], 0x50000
	global_load_dwordx4 v[152:155], v[144:145], off
	global_load_dwordx4 v[156:159], v[144:145], off offset:64
	global_load_dwordx4 v[160:163], v[144:145], off offset:512
	global_load_dwordx4 v[164:167], v[144:145], off offset:576
	v_mov_b64_e32 v[248:249], v[142:143]
	v_mov_b64_e32 v[140:141], v[142:143]
	global_load_dwordx4 v[168:171], v[248:249], off
	global_load_dwordx4 v[172:175], v[248:249], off offset:64
	global_load_dwordx4 v[176:179], v[248:249], off offset:512
	global_load_dwordx4 v[204:207], v[248:249], off offset:576
	v_lshl_add_u64 v[248:249], v[248:249], 0, s[94:95]
	global_load_dwordx4 v[208:211], v[248:249], off
	global_load_dwordx4 v[212:215], v[248:249], off offset:64
	global_load_dwordx4 v[216:219], v[248:249], off offset:512
	global_load_dwordx4 v[220:223], v[248:249], off offset:576
	v_lshl_add_u64 v[248:249], v[248:249], 0, s[94:95]
	global_load_dwordx4 v[224:227], v[248:249], off
	global_load_dwordx4 v[228:231], v[248:249], off offset:64
	global_load_dwordx4 v[232:235], v[248:249], off offset:512
	global_load_dwordx4 v[236:239], v[248:249], off offset:576
	v_lshl_add_u64 v[248:249], v[248:249], 0, s[94:95]
	global_load_dwordx4 v[240:243], v[248:249], off
	global_load_dwordx4 v[244:247], v[248:249], off offset:64
	s_waitcnt vmcnt(13)
	v_pk_fma_f32 v[126:127], v[126:127], v[154:155], v[170:171]
	v_pk_fma_f32 v[124:125], v[124:125], v[152:153], v[168:169]
	global_load_dwordx4 v[168:171], v[248:249], off offset:512
	s_waitcnt vmcnt(13)
	v_pk_fma_f32 v[122:123], v[122:123], v[158:159], v[174:175]
	v_pk_fma_f32 v[120:121], v[120:121], v[156:157], v[172:173]
	global_load_dwordx4 v[172:175], v[248:249], off offset:576
	s_waitcnt vmcnt(13)
	v_pk_fma_f32 v[94:95], v[94:95], v[162:163], v[178:179]
	v_pk_fma_f32 v[92:93], v[92:93], v[160:161], v[176:177]
	v_lshl_add_u64 v[248:249], v[248:249], 0, s[96:97]
	global_load_dwordx4 v[176:179], v[248:249], off
	s_waitcnt vmcnt(13)
	v_pk_fma_f32 v[90:91], v[90:91], v[166:167], v[206:207]
	v_pk_fma_f32 v[88:89], v[88:89], v[164:165], v[204:205]
	global_load_dwordx4 v[204:207], v[248:249], off offset:64
	s_waitcnt vmcnt(13)
	v_pk_fma_f32 v[118:119], v[118:119], v[154:155], v[210:211]
	v_pk_fma_f32 v[116:117], v[116:117], v[152:153], v[208:209]
	global_load_dwordx4 v[208:211], v[248:249], off offset:512
	s_waitcnt vmcnt(13)
	v_pk_fma_f32 v[114:115], v[114:115], v[158:159], v[214:215]
	v_pk_fma_f32 v[112:113], v[112:113], v[156:157], v[212:213]
	global_load_dwordx4 v[212:215], v[248:249], off offset:576
	s_waitcnt vmcnt(13)
	v_pk_fma_f32 v[86:87], v[86:87], v[162:163], v[218:219]
	v_pk_fma_f32 v[84:85], v[84:85], v[160:161], v[216:217]
	v_lshl_add_u64 v[248:249], v[248:249], 0, s[94:95]
	global_load_dwordx4 v[216:219], v[248:249], off
	s_waitcnt vmcnt(13)
	v_pk_fma_f32 v[82:83], v[82:83], v[166:167], v[222:223]
	v_pk_fma_f32 v[80:81], v[80:81], v[164:165], v[220:221]
	global_load_dwordx4 v[220:223], v[248:249], off offset:64
	s_waitcnt vmcnt(13)
	v_pk_fma_f32 v[110:111], v[110:111], v[154:155], v[226:227]
	v_pk_fma_f32 v[108:109], v[108:109], v[152:153], v[224:225]
	global_load_dwordx4 v[224:227], v[248:249], off offset:512
	s_waitcnt vmcnt(13)
	v_pk_fma_f32 v[106:107], v[106:107], v[158:159], v[230:231]
	v_pk_fma_f32 v[104:105], v[104:105], v[156:157], v[228:229]
	global_load_dwordx4 v[228:231], v[248:249], off offset:576
	s_waitcnt vmcnt(13)
	v_pk_fma_f32 v[78:79], v[78:79], v[162:163], v[234:235]
	v_pk_fma_f32 v[76:77], v[76:77], v[160:161], v[232:233]
	v_lshl_add_u64 v[248:249], v[248:249], 0, s[94:95]
	global_load_dwordx4 v[232:235], v[248:249], off
	s_waitcnt vmcnt(13)
	v_pk_fma_f32 v[74:75], v[74:75], v[166:167], v[238:239]
	v_pk_fma_f32 v[72:73], v[72:73], v[164:165], v[236:237]
	global_load_dwordx4 v[236:239], v[248:249], off offset:64
	s_waitcnt vmcnt(13)
	v_pk_fma_f32 v[102:103], v[102:103], v[154:155], v[242:243]
	v_pk_fma_f32 v[100:101], v[100:101], v[152:153], v[240:241]
	global_load_dwordx4 v[240:243], v[248:249], off offset:512
	s_waitcnt vmcnt(13)
	v_pk_fma_f32 v[98:99], v[98:99], v[158:159], v[246:247]
	v_pk_fma_f32 v[96:97], v[96:97], v[156:157], v[244:245]
	global_load_dwordx4 v[244:247], v[248:249], off offset:576
	s_waitcnt vmcnt(13)
	v_pk_fma_f32 v[70:71], v[70:71], v[162:163], v[170:171]
	v_pk_fma_f32 v[68:69], v[68:69], v[160:161], v[168:169]
	v_lshl_add_u64 v[248:249], v[248:249], 0, s[94:95]
	global_load_dwordx4 v[168:171], v[248:249], off
	s_waitcnt vmcnt(13)
	v_pk_fma_f32 v[66:67], v[66:67], v[166:167], v[174:175]
	v_pk_fma_f32 v[64:65], v[64:65], v[164:165], v[172:173]
	global_load_dwordx4 v[172:175], v[248:249], off offset:64
	s_waitcnt vmcnt(13)
	v_pk_fma_f32 v[62:63], v[62:63], v[154:155], v[178:179]
	v_pk_fma_f32 v[60:61], v[60:61], v[152:153], v[176:177]
	global_load_dwordx4 v[176:179], v[248:249], off offset:512
	s_waitcnt vmcnt(13)
	v_pk_fma_f32 v[58:59], v[58:59], v[158:159], v[206:207]
	v_pk_fma_f32 v[56:57], v[56:57], v[156:157], v[204:205]
	global_load_dwordx4 v[204:207], v[248:249], off offset:576
	s_waitcnt vmcnt(13)
	v_pk_fma_f32 v[30:31], v[30:31], v[162:163], v[210:211]
	v_pk_fma_f32 v[28:29], v[28:29], v[160:161], v[208:209]
	s_waitcnt vmcnt(12)
	v_pk_fma_f32 v[26:27], v[26:27], v[166:167], v[214:215]
	v_pk_fma_f32 v[24:25], v[24:25], v[164:165], v[212:213]
	s_waitcnt vmcnt(11)
	v_pk_fma_f32 v[54:55], v[54:55], v[154:155], v[218:219]
	v_pk_fma_f32 v[52:53], v[52:53], v[152:153], v[216:217]
	s_waitcnt vmcnt(10)
	v_pk_fma_f32 v[50:51], v[50:51], v[158:159], v[222:223]
	v_pk_fma_f32 v[48:49], v[48:49], v[156:157], v[220:221]
	s_waitcnt vmcnt(9)
	v_pk_fma_f32 v[22:23], v[22:23], v[162:163], v[226:227]
	v_pk_fma_f32 v[20:21], v[20:21], v[160:161], v[224:225]
	s_waitcnt vmcnt(8)
	v_pk_fma_f32 v[18:19], v[18:19], v[166:167], v[230:231]
	v_pk_fma_f32 v[16:17], v[16:17], v[164:165], v[228:229]
	s_waitcnt vmcnt(7)
	v_pk_fma_f32 v[46:47], v[46:47], v[154:155], v[234:235]
	v_pk_fma_f32 v[44:45], v[44:45], v[152:153], v[232:233]
	s_waitcnt vmcnt(6)
	v_pk_fma_f32 v[42:43], v[42:43], v[158:159], v[238:239]
	v_pk_fma_f32 v[40:41], v[40:41], v[156:157], v[236:237]
	s_waitcnt vmcnt(5)
	v_pk_fma_f32 v[14:15], v[14:15], v[162:163], v[242:243]
	v_pk_fma_f32 v[12:13], v[12:13], v[160:161], v[240:241]
	s_waitcnt vmcnt(4)
	v_pk_fma_f32 v[10:11], v[10:11], v[166:167], v[246:247]
	v_pk_fma_f32 v[8:9], v[8:9], v[164:165], v[244:245]
	s_waitcnt vmcnt(3)
	v_pk_fma_f32 v[38:39], v[38:39], v[154:155], v[170:171]
	v_pk_fma_f32 v[36:37], v[36:37], v[152:153], v[168:169]
	s_waitcnt vmcnt(2)
	v_pk_fma_f32 v[34:35], v[34:35], v[158:159], v[174:175]
	v_pk_fma_f32 v[32:33], v[32:33], v[156:157], v[172:173]
	s_waitcnt vmcnt(1)
	v_pk_fma_f32 v[6:7], v[6:7], v[162:163], v[178:179]
	v_pk_fma_f32 v[4:5], v[4:5], v[160:161], v[176:177]
	s_waitcnt vmcnt(0)
	v_pk_fma_f32 v[2:3], v[2:3], v[166:167], v[206:207]
	v_pk_fma_f32 v[0:1], v[0:1], v[164:165], v[204:205]
	global_store_dwordx4 v[140:141], v[124:127], off
	global_store_dwordx4 v[140:141], v[120:123], off offset:64
	global_store_dwordx4 v[140:141], v[92:95], off offset:512
	global_store_dwordx4 v[140:141], v[88:91], off offset:576
	v_lshl_add_u64 v[140:141], v[140:141], 0, s[94:95]
	global_store_dwordx4 v[140:141], v[116:119], off
	global_store_dwordx4 v[140:141], v[112:115], off offset:64
	global_store_dwordx4 v[140:141], v[84:87], off offset:512
	global_store_dwordx4 v[140:141], v[80:83], off offset:576
	v_lshl_add_u64 v[140:141], v[140:141], 0, s[94:95]
	global_store_dwordx4 v[140:141], v[108:111], off
	global_store_dwordx4 v[140:141], v[104:107], off offset:64
	global_store_dwordx4 v[140:141], v[76:79], off offset:512
	global_store_dwordx4 v[140:141], v[72:75], off offset:576
	v_lshl_add_u64 v[140:141], v[140:141], 0, s[94:95]
	global_store_dwordx4 v[140:141], v[100:103], off
	global_store_dwordx4 v[140:141], v[96:99], off offset:64
	global_store_dwordx4 v[140:141], v[68:71], off offset:512
	global_store_dwordx4 v[140:141], v[64:67], off offset:576
	v_lshl_add_u64 v[140:141], v[140:141], 0, s[96:97]
	global_store_dwordx4 v[140:141], v[60:63], off
	global_store_dwordx4 v[140:141], v[56:59], off offset:64
	global_store_dwordx4 v[140:141], v[28:31], off offset:512
	global_store_dwordx4 v[140:141], v[24:27], off offset:576
	v_lshl_add_u64 v[140:141], v[140:141], 0, s[94:95]
	global_store_dwordx4 v[140:141], v[52:55], off
	global_store_dwordx4 v[140:141], v[48:51], off offset:64
	global_store_dwordx4 v[140:141], v[20:23], off offset:512
	global_store_dwordx4 v[140:141], v[16:19], off offset:576
	v_lshl_add_u64 v[140:141], v[140:141], 0, s[94:95]
	global_store_dwordx4 v[140:141], v[44:47], off
	global_store_dwordx4 v[140:141], v[40:43], off offset:64
	global_store_dwordx4 v[140:141], v[12:15], off offset:512
	global_store_dwordx4 v[140:141], v[8:11], off offset:576
	v_lshl_add_u64 v[140:141], v[140:141], 0, s[94:95]
	global_store_dwordx4 v[140:141], v[36:39], off
	global_store_dwordx4 v[140:141], v[32:35], off offset:64
	global_store_dwordx4 v[140:141], v[4:7], off offset:512
	global_store_dwordx4 v[140:141], v[0:3], off offset:576
	s_mov_b32 s25, s10
	s_mov_b32 s26, s12
	s_andn2_b64 vcc, exec, s[8:9]
	s_cbranch_vccz .LBB0_1843

.LBB0_2026:
	v_add_u32_e32 v146, s25, v133
	v_min_i32_e32 v144, 0x8000, v146
	v_readlane_b32 s48, v251, 19
	v_ashrrev_i32_e32 v144, 12, v144
	v_readlane_b32 s52, v251, 23
	v_readlane_b32 s53, v251, 24
	v_readlane_b32 s54, v251, 25
	v_readlane_b32 s55, v251, 26
	v_readlane_b32 s56, v251, 27
	v_readlane_b32 s57, v251, 28
	v_readlane_b32 s58, v251, 29
	v_readlane_b32 s59, v251, 30
	v_add_u32_e32 v140, s24, v149
	s_mov_b32 s24, 0x8000
	v_mul_i32_i24_e32 v144, 0x2400, v144
	v_readlane_b32 s60, v251, 31
	v_readlane_b32 s61, v251, 32
	v_readlane_b32 s62, v251, 33
	v_readlane_b32 s63, v251, 34
	s_mov_b64 s[52:53], s[56:57]
	v_readlane_b32 s30, v254, 27
	v_ashrrev_i32_e32 v141, 31, v140
	v_add_u32_e32 v142, 0xffff8000, v146
	v_ashrrev_i32_e32 v143, 31, v146
	v_cmp_gt_i32_e32 vcc, s24, v146
	v_ashrrev_i32_e32 v145, 31, v144
	s_mov_b64 s[54:55], s[58:59]
	v_readlane_b32 s31, v254, 28
	v_cndmask_b32_e32 v143, 0, v143, vcc
	v_cndmask_b32_e32 v142, v142, v146, vcc
	v_mov_b32_e32 v147, s55
	v_mov_b32_e32 v151, s53
	v_mov_b32_e32 v152, s54
	v_mov_b32_e32 v153, s52
	v_lshl_add_u64 v[144:145], v[144:145], 2, s[30:31]
	v_lshlrev_b64 v[140:141], 2, v[140:141]
	v_lshlrev_b64 v[142:143], 12, v[142:143]
	v_cndmask_b32_e32 v155, v147, v151, vcc
	v_cndmask_b32_e32 v154, v152, v153, vcc
	v_lshl_add_u64 v[144:145], v[144:145], 0, v[140:141]
	v_lshl_add_u64 v[142:143], v[154:155], 0, v[142:143]
	v_add_co_u32_e32 v154, vcc, s24, v144
	v_lshl_add_u64 v[142:143], v[142:143], 0, v[140:141]
	s_nop 0
	v_addc_co_u32_e32 v155, vcc, 0, v145, vcc
	s_mov_b64 s[28:29], 0x8000
	v_lshl_add_u64 v[144:145], v[144:145], 0, s[28:29]
	s_movk_i32 s25, 0x7ff0
	v_cmp_gt_i32_e32 vcc, s25, v146
	s_movk_i32 s26, 0x7fe0
	s_movk_i32 s27, 0x7fd0
	v_readlane_b32 s49, v251, 20
	v_readlane_b32 s50, v251, 21
	v_readlane_b32 s51, v251, 22
	s_mov_b64 s[56:57], s[60:61]
	s_mov_b64 s[58:59], s[62:63]
	v_readlane_b32 s48, v251, 3
	v_readlane_b32 s49, v251, 4
	v_readlane_b32 s52, v251, 7
	v_readlane_b32 s53, v251, 8
	v_readlane_b32 s60, v251, 15
	v_readlane_b32 s61, v251, 16
	v_readlane_b32 s50, v251, 5
	v_readlane_b32 s51, v251, 6
	v_readlane_b32 s54, v251, 9
	v_readlane_b32 s55, v251, 10
	v_readlane_b32 s56, v251, 11
	v_readlane_b32 s57, v251, 12
	v_readlane_b32 s58, v251, 13
	v_readlane_b32 s59, v251, 14
	v_readlane_b32 s62, v251, 17
	v_readlane_b32 s63, v251, 18
	s_mov_b64 s[94:95], 0x10000
	s_mov_b64 s[96:97], 0x50000
	global_load_dwordx4 v[152:155], v[144:145], off
	global_load_dwordx4 v[156:159], v[144:145], off offset:64
	global_load_dwordx4 v[160:163], v[144:145], off offset:512
	global_load_dwordx4 v[164:167], v[144:145], off offset:576
	v_mov_b64_e32 v[248:249], v[142:143]
	v_mov_b64_e32 v[140:141], v[142:143]
	global_load_dwordx4 v[168:171], v[248:249], off
	global_load_dwordx4 v[172:175], v[248:249], off offset:64
	global_load_dwordx4 v[176:179], v[248:249], off offset:512
	global_load_dwordx4 v[204:207], v[248:249], off offset:576
	v_lshl_add_u64 v[248:249], v[248:249], 0, s[94:95]
	global_load_dwordx4 v[208:211], v[248:249], off
	global_load_dwordx4 v[212:215], v[248:249], off offset:64
	global_load_dwordx4 v[216:219], v[248:249], off offset:512
	global_load_dwordx4 v[220:223], v[248:249], off offset:576
	v_lshl_add_u64 v[248:249], v[248:249], 0, s[94:95]
	global_load_dwordx4 v[224:227], v[248:249], off
	global_load_dwordx4 v[228:231], v[248:249], off offset:64
	global_load_dwordx4 v[232:235], v[248:249], off offset:512
	global_load_dwordx4 v[236:239], v[248:249], off offset:576
	v_lshl_add_u64 v[248:249], v[248:249], 0, s[94:95]
	global_load_dwordx4 v[240:243], v[248:249], off
	global_load_dwordx4 v[244:247], v[248:249], off offset:64
	s_waitcnt vmcnt(13)
	v_pk_mul_f32 v[154:155], v[154:155], 0.5 op_sel_hi:[1,0]
	v_pk_mul_f32 v[152:153], v[152:153], 0.5 op_sel_hi:[1,0]
	v_pk_mul_f32 v[158:159], v[158:159], 0.5 op_sel_hi:[1,0]
	v_pk_mul_f32 v[156:157], v[156:157], 0.5 op_sel_hi:[1,0]
	v_pk_mul_f32 v[162:163], v[162:163], 0.5 op_sel_hi:[1,0]
	v_pk_mul_f32 v[160:161], v[160:161], 0.5 op_sel_hi:[1,0]
	v_pk_mul_f32 v[166:167], v[166:167], 0.5 op_sel_hi:[1,0]
	v_pk_mul_f32 v[164:165], v[164:165], 0.5 op_sel_hi:[1,0]
	v_pk_fma_f32 v[126:127], v[126:127], v[154:155], v[170:171]
	v_pk_fma_f32 v[124:125], v[124:125], v[152:153], v[168:169]
	global_load_dwordx4 v[168:171], v[248:249], off offset:512
	s_waitcnt vmcnt(13)
	v_pk_fma_f32 v[122:123], v[122:123], v[158:159], v[174:175]
	v_pk_fma_f32 v[120:121], v[120:121], v[156:157], v[172:173]
	global_load_dwordx4 v[172:175], v[248:249], off offset:576
	s_waitcnt vmcnt(13)
	v_pk_fma_f32 v[98:99], v[98:99], v[162:163], v[178:179]
	v_pk_fma_f32 v[96:97], v[96:97], v[160:161], v[176:177]
	v_lshl_add_u64 v[248:249], v[248:249], 0, s[96:97]
	global_load_dwordx4 v[176:179], v[248:249], off
	s_waitcnt vmcnt(13)
	v_pk_fma_f32 v[90:91], v[90:91], v[166:167], v[206:207]
	v_pk_fma_f32 v[88:89], v[88:89], v[164:165], v[204:205]
	global_load_dwordx4 v[204:207], v[248:249], off offset:64
	s_waitcnt vmcnt(13)
	v_pk_fma_f32 v[118:119], v[118:119], v[154:155], v[210:211]
	v_pk_fma_f32 v[116:117], v[116:117], v[152:153], v[208:209]
	global_load_dwordx4 v[208:211], v[248:249], off offset:512
	s_waitcnt vmcnt(13)
	v_pk_fma_f32 v[114:115], v[114:115], v[158:159], v[214:215]
	v_pk_fma_f32 v[112:113], v[112:113], v[156:157], v[212:213]
	global_load_dwordx4 v[212:215], v[248:249], off offset:576
	s_waitcnt vmcnt(13)
	v_pk_fma_f32 v[86:87], v[86:87], v[162:163], v[218:219]
	v_pk_fma_f32 v[84:85], v[84:85], v[160:161], v[216:217]
	v_lshl_add_u64 v[248:249], v[248:249], 0, s[94:95]
	global_load_dwordx4 v[216:219], v[248:249], off
	s_waitcnt vmcnt(13)
	v_pk_fma_f32 v[82:83], v[82:83], v[166:167], v[222:223]
	v_pk_fma_f32 v[80:81], v[80:81], v[164:165], v[220:221]
	global_load_dwordx4 v[220:223], v[248:249], off offset:64
	s_waitcnt vmcnt(13)
	v_pk_fma_f32 v[110:111], v[110:111], v[154:155], v[226:227]
	v_pk_fma_f32 v[108:109], v[108:109], v[152:153], v[224:225]
	global_load_dwordx4 v[224:227], v[248:249], off offset:512
	s_waitcnt vmcnt(13)
	v_pk_fma_f32 v[106:107], v[106:107], v[158:159], v[230:231]
	v_pk_fma_f32 v[104:105], v[104:105], v[156:157], v[228:229]
	global_load_dwordx4 v[228:231], v[248:249], off offset:576
	s_waitcnt vmcnt(13)
	v_pk_fma_f32 v[78:79], v[78:79], v[162:163], v[234:235]
	v_pk_fma_f32 v[76:77], v[76:77], v[160:161], v[232:233]
	v_lshl_add_u64 v[248:249], v[248:249], 0, s[94:95]
	global_load_dwordx4 v[232:235], v[248:249], off
	s_waitcnt vmcnt(13)
	v_pk_fma_f32 v[74:75], v[74:75], v[166:167], v[238:239]
	v_pk_fma_f32 v[72:73], v[72:73], v[164:165], v[236:237]
	global_load_dwordx4 v[236:239], v[248:249], off offset:64
	s_waitcnt vmcnt(13)
	v_pk_fma_f32 v[102:103], v[102:103], v[154:155], v[242:243]
	v_pk_fma_f32 v[100:101], v[100:101], v[152:153], v[240:241]
	global_load_dwordx4 v[240:243], v[248:249], off offset:512
	s_waitcnt vmcnt(13)
	v_pk_fma_f32 v[94:95], v[94:95], v[158:159], v[246:247]
	v_pk_fma_f32 v[92:93], v[92:93], v[156:157], v[244:245]
	global_load_dwordx4 v[244:247], v[248:249], off offset:576
	s_waitcnt vmcnt(13)
	v_pk_fma_f32 v[70:71], v[70:71], v[162:163], v[170:171]
	v_pk_fma_f32 v[68:69], v[68:69], v[160:161], v[168:169]
	v_lshl_add_u64 v[248:249], v[248:249], 0, s[94:95]
	global_load_dwordx4 v[168:171], v[248:249], off
	s_waitcnt vmcnt(13)
	v_pk_fma_f32 v[62:63], v[62:63], v[166:167], v[174:175]
	v_pk_fma_f32 v[60:61], v[60:61], v[164:165], v[172:173]
	global_load_dwordx4 v[172:175], v[248:249], off offset:64
	s_waitcnt vmcnt(13)
	v_pk_fma_f32 v[66:67], v[66:67], v[154:155], v[178:179]
	v_pk_fma_f32 v[64:65], v[64:65], v[152:153], v[176:177]
	global_load_dwordx4 v[176:179], v[248:249], off offset:512
	s_waitcnt vmcnt(13)
	v_pk_fma_f32 v[58:59], v[58:59], v[158:159], v[206:207]
	v_pk_fma_f32 v[56:57], v[56:57], v[156:157], v[204:205]
	global_load_dwordx4 v[204:207], v[248:249], off offset:576
	s_waitcnt vmcnt(13)
	v_pk_fma_f32 v[30:31], v[30:31], v[162:163], v[210:211]
	v_pk_fma_f32 v[28:29], v[28:29], v[160:161], v[208:209]
	s_waitcnt vmcnt(12)
	v_pk_fma_f32 v[26:27], v[26:27], v[166:167], v[214:215]
	v_pk_fma_f32 v[24:25], v[24:25], v[164:165], v[212:213]
	s_waitcnt vmcnt(11)
	v_pk_fma_f32 v[54:55], v[54:55], v[154:155], v[218:219]
	v_pk_fma_f32 v[52:53], v[52:53], v[152:153], v[216:217]
	s_waitcnt vmcnt(10)
	v_pk_fma_f32 v[50:51], v[50:51], v[158:159], v[222:223]
	v_pk_fma_f32 v[48:49], v[48:49], v[156:157], v[220:221]
	s_waitcnt vmcnt(9)
	v_pk_fma_f32 v[22:23], v[22:23], v[162:163], v[226:227]
	v_pk_fma_f32 v[20:21], v[20:21], v[160:161], v[224:225]
	s_waitcnt vmcnt(8)
	v_pk_fma_f32 v[18:19], v[18:19], v[166:167], v[230:231]
	v_pk_fma_f32 v[16:17], v[16:17], v[164:165], v[228:229]
	s_waitcnt vmcnt(7)
	v_pk_fma_f32 v[46:47], v[46:47], v[154:155], v[234:235]
	v_pk_fma_f32 v[44:45], v[44:45], v[152:153], v[232:233]
	s_waitcnt vmcnt(6)
	v_pk_fma_f32 v[42:43], v[42:43], v[158:159], v[238:239]
	v_pk_fma_f32 v[40:41], v[40:41], v[156:157], v[236:237]
	s_waitcnt vmcnt(5)
	v_pk_fma_f32 v[14:15], v[14:15], v[162:163], v[242:243]
	v_pk_fma_f32 v[12:13], v[12:13], v[160:161], v[240:241]
	s_waitcnt vmcnt(4)
	v_pk_fma_f32 v[10:11], v[10:11], v[166:167], v[246:247]
	v_pk_fma_f32 v[8:9], v[8:9], v[164:165], v[244:245]
	s_waitcnt vmcnt(3)
	v_pk_fma_f32 v[38:39], v[38:39], v[154:155], v[170:171]
	v_pk_fma_f32 v[36:37], v[36:37], v[152:153], v[168:169]
	s_waitcnt vmcnt(2)
	v_pk_fma_f32 v[34:35], v[34:35], v[158:159], v[174:175]
	v_pk_fma_f32 v[32:33], v[32:33], v[156:157], v[172:173]
	s_waitcnt vmcnt(1)
	v_pk_fma_f32 v[6:7], v[6:7], v[162:163], v[178:179]
	v_pk_fma_f32 v[4:5], v[4:5], v[160:161], v[176:177]
	s_waitcnt vmcnt(0)
	v_pk_fma_f32 v[2:3], v[2:3], v[166:167], v[206:207]
	v_pk_fma_f32 v[0:1], v[0:1], v[164:165], v[204:205]
	global_store_dwordx4 v[140:141], v[124:127], off
	global_store_dwordx4 v[140:141], v[120:123], off offset:64
	global_store_dwordx4 v[140:141], v[96:99], off offset:512
	global_store_dwordx4 v[140:141], v[88:91], off offset:576
	v_lshl_add_u64 v[140:141], v[140:141], 0, s[94:95]
	global_store_dwordx4 v[140:141], v[116:119], off
	global_store_dwordx4 v[140:141], v[112:115], off offset:64
	global_store_dwordx4 v[140:141], v[84:87], off offset:512
	global_store_dwordx4 v[140:141], v[80:83], off offset:576
	v_lshl_add_u64 v[140:141], v[140:141], 0, s[94:95]
	global_store_dwordx4 v[140:141], v[108:111], off
	global_store_dwordx4 v[140:141], v[104:107], off offset:64
	global_store_dwordx4 v[140:141], v[76:79], off offset:512
	global_store_dwordx4 v[140:141], v[72:75], off offset:576
	v_lshl_add_u64 v[140:141], v[140:141], 0, s[94:95]
	global_store_dwordx4 v[140:141], v[100:103], off
	global_store_dwordx4 v[140:141], v[92:95], off offset:64
	global_store_dwordx4 v[140:141], v[68:71], off offset:512
	global_store_dwordx4 v[140:141], v[60:63], off offset:576
	v_lshl_add_u64 v[140:141], v[140:141], 0, s[96:97]
	global_store_dwordx4 v[140:141], v[64:67], off
	global_store_dwordx4 v[140:141], v[56:59], off offset:64
	global_store_dwordx4 v[140:141], v[28:31], off offset:512
	global_store_dwordx4 v[140:141], v[24:27], off offset:576
	v_lshl_add_u64 v[140:141], v[140:141], 0, s[94:95]
	global_store_dwordx4 v[140:141], v[52:55], off
	global_store_dwordx4 v[140:141], v[48:51], off offset:64
	global_store_dwordx4 v[140:141], v[20:23], off offset:512
	global_store_dwordx4 v[140:141], v[16:19], off offset:576
	v_lshl_add_u64 v[140:141], v[140:141], 0, s[94:95]
	global_store_dwordx4 v[140:141], v[44:47], off
	global_store_dwordx4 v[140:141], v[40:43], off offset:64
	global_store_dwordx4 v[140:141], v[12:15], off offset:512
	global_store_dwordx4 v[140:141], v[8:11], off offset:576
	v_lshl_add_u64 v[140:141], v[140:141], 0, s[94:95]
	global_store_dwordx4 v[140:141], v[36:39], off
	global_store_dwordx4 v[140:141], v[32:35], off offset:64
	global_store_dwordx4 v[140:141], v[4:7], off offset:512
	global_store_dwordx4 v[140:141], v[0:3], off offset:576
	s_mov_b32 s25, s23
	s_mov_b32 s24, s22
	s_andn2_b64 vcc, exec, s[10:11]
	s_cbranch_vccz .LBB0_2038
